# stagger: waves 4-7 run own loop copy with PV MFMAs deferred past the stage barrier (operands kept in regs); A QK prio1, A PV prio0, B PV+QK prio1
# speedup vs baseline: 1.0628x; 1.0011x over previous
; #define LAS __attribute__((address_space(3)))
; #define MFMA32(a, b, c) __builtin_amdgcn_mfma_f32_32x32x16_bf16((a), (b), (c), 0, 0, 0)
; #define AT_LOAD(st) do { _Pragma("unroll") for (int e = 0; e < 3; ++e) pk[e] = *(const u32x4*)(kbase + (size_t)((st) * 64 + krow[e]) * 768 + kcol[e] * 8); \
;         _Pragma("unroll") for (int e = 0; e < 2; ++e) { const int c = tid + 512 * e; pv[e] = *(const u32x4*)(vbase + (size_t)(c >> 3) * SEQ + (st) * 64 + (c & 7) * 8); } } while (0)
; DI void attn_unit(const Params& p, int b, int h, int qb, LAS unsigned char* lds, int tid, int lane, int wave) {
;     ...
;     for (int st = 0; st < nst; ++st) {
;         const int buf = st & 1;
;         if (st + 1 < nst) AT_LOAD(st + 1);
;         const int kb = st * 64 + g * 32;
;         if (kb <= qr0 + 31) {
;             f32x16 s;
; #pragma unroll
;             for (int j = 0; j < 16; ++j) s[j] = 0.f;
;             const LAS unsigned char* kp = lds + AT_K0 + buf * AT_KB + (g * 32 + r) * 400 + hh * 16;
;             bf16x8 kf[12];
; #pragma unroll
;             for (int kk = 0; kk < 12; ++kk) kf[kk] = *(const LAS bf16x8*)(kp + kk * 32);
;             __builtin_amdgcn_sched_barrier(0);
;             __builtin_amdgcn_s_setprio(1);
; #pragma unroll
;             for (int kk = 0; kk < 12; ++kk) s = MFMA32(kf[kk], qf[kk], s);
;             __builtin_amdgcn_s_setprio(0);
;             const LAS unsigned char* vp = lds + AT_V0 + buf * AT_VB + r * 136 + (g * 32 + 4 * hh) * 2;
;             bf16x8 vf[2][4];
; #pragma unroll
;             for (int ks = 0; ks < 2; ++ks)
; #pragma unroll
;                 for (int blk = 0; blk < 4; ++blk) {
;                     const s16x4 lo = *(const LAS s16x4*)(vp + blk * 32 * 136 + ks * 32), hi = *(const LAS s16x4*)(vp + blk * 32 * 136 + ks * 32 + 16);
;                     vf[ks][blk] = __builtin_shufflevector(lo, hi, 0, 1, 2, 3, 4, 5, 6, 7);
;                 }
;             __builtin_amdgcn_sched_barrier(0);
;             if (kb + 31 > qr0) {
;                 const int qa = qr0 + r - kb - 4 * hh;
; #pragma unroll
;                 for (int j = 0; j < 16; ++j) if ((j & 3) + 8 * (j >> 2) > qa) s[j] = -INFINITY;
.Lal1_done:
	s_mul_i32 s0, s66, 0x600
	s_mul_i32 s1, s2, 0x180
	s_add_u32 s0, s0, s1
	s_add_u32 s0, s0, 0xce18000
	s_add_u32 s98, s0, s50
	s_addc_u32 s99, 0, s51
	s_add_u32 s0, s92, 0xe600080
	s_add_u32 s100, s0, s50
	s_addc_u32 s101, 0, s51
	s_cmp_lg_u32 s21, 0
	s_cbranch_scc1 .Lsb1_first
	s_branch .LBB0_429
.Lsb1_first:
	s_setprio 1
	global_load_dwordx4 v[130:133], v184, s[100:101]
	global_load_dwordx4 v[134:137], v185, s[100:101]
	global_load_dwordx4 v[138:141], v186, s[100:101]
	global_load_dwordx4 v[142:145], v187, s[100:101]
	s_and_b32 s78, s63, 1
	s_add_i32 s0, s56, s62
	s_cmp_gt_i32 s0, s57
	s_cbranch_scc1 .Lsb1_skipd
	s_branch .Lsb1_qk
.Lsb1_top:
	s_setprio 1
	v_mfma_f32_32x32x16_bf16 v[50:65], v[166:169], v[66:69], v[50:65]
	v_mfma_f32_32x32x16_bf16 v[34:49], v[170:173], v[66:69], v[34:49]
	v_mfma_f32_32x32x16_bf16 v[18:33], v[178:181], v[66:69], v[18:33]
	v_mfma_f32_32x32x16_bf16 v[2:17], v[174:177], v[66:69], v[2:17]
	v_mfma_f32_32x32x16_bf16 v[50:65], v[150:153], v[70:73], v[50:65]
	v_mfma_f32_32x32x16_bf16 v[34:49], v[162:165], v[70:73], v[34:49]
	v_mfma_f32_32x32x16_bf16 v[18:33], v[158:161], v[70:73], v[18:33]
	v_mfma_f32_32x32x16_bf16 v[2:17], v[154:157], v[70:73], v[2:17]
	global_load_dwordx4 v[130:133], v184, s[100:101]
	global_load_dwordx4 v[134:137], v185, s[100:101]
	global_load_dwordx4 v[138:141], v186, s[100:101]
	global_load_dwordx4 v[142:145], v187, s[100:101]
	s_and_b32 s78, s63, 1
	s_add_i32 s0, s56, s62
	s_cmp_gt_i32 s0, s57
	s_cbranch_scc1 .Lsb1_skipd
.Lsb1_qk:
	s_mul_i32 s1, s78, 0x6400
	v_add_u32_e32 v0, s1, v216
	ds_read_b128 v[66:69], v0
	ds_read_b128 v[150:153], v0 offset:32
	ds_read_b128 v[154:157], v0 offset:64
	ds_read_b128 v[158:161], v0 offset:96
	ds_read_b128 v[162:165], v0 offset:128
	ds_read_b128 v[166:169], v0 offset:160
	ds_read_b128 v[170:173], v0 offset:192
	ds_read_b128 v[174:177], v0 offset:224
	ds_read_b128 v[178:181], v0 offset:256
	ds_read_b128 v[194:197], v0 offset:288
	ds_read_b128 v[198:201], v0 offset:320
	ds_read_b128 v[218:221], v0 offset:352
	s_waitcnt lgkmcnt(11)
	v_mfma_f32_32x32x16_bf16 v[66:81], v[66:69], v[126:129], v[230:245]
	s_mul_i32 s1, s78, 0x4800
	v_add_u32_e32 v0, s1, v206
	s_waitcnt lgkmcnt(10)
	v_mfma_f32_32x32x16_bf16 v[66:81], v[150:153], v[122:125], v[66:81]
	s_waitcnt lgkmcnt(9)
	v_mfma_f32_32x32x16_bf16 v[66:81], v[154:157], v[118:121], v[66:81]
	s_waitcnt lgkmcnt(8)
	v_mfma_f32_32x32x16_bf16 v[66:81], v[158:161], v[114:117], v[66:81]
	s_waitcnt lgkmcnt(7)
	v_mfma_f32_32x32x16_bf16 v[66:81], v[162:165], v[110:113], v[66:81]
	s_waitcnt lgkmcnt(6)
	v_mfma_f32_32x32x16_bf16 v[66:81], v[166:169], v[106:109], v[66:81]
	ds_read_b128 v[166:169], v0 offset:51200
	ds_read_b128 v[150:153], v0 offset:51232
	s_waitcnt lgkmcnt(7)
	v_mfma_f32_32x32x16_bf16 v[66:81], v[170:173], v[102:105], v[66:81]
	ds_read_b128 v[170:173], v0 offset:55808
	s_waitcnt lgkmcnt(7)
	v_mfma_f32_32x32x16_bf16 v[66:81], v[174:177], v[98:101], v[66:81]
	s_waitcnt lgkmcnt(6)
	v_mfma_f32_32x32x16_bf16 v[66:81], v[178:181], v[94:97], v[66:81]
	ds_read_b128 v[178:181], v0 offset:60416
	ds_read_b128 v[174:177], v0 offset:65024
	ds_read_b128 v[162:165], v0 offset:55840
	ds_read_b128 v[158:161], v0 offset:60448
	ds_read_b128 v[154:157], v0 offset:65056
	s_waitcnt lgkmcnt(10)
	v_mfma_f32_32x32x16_bf16 v[66:81], v[194:197], v[90:93], v[66:81]
	s_waitcnt lgkmcnt(9)
	v_mfma_f32_32x32x16_bf16 v[66:81], v[198:201], v[86:89], v[66:81]
	s_waitcnt lgkmcnt(8)
	v_mfma_f32_32x32x16_bf16 v[66:81], v[218:221], v[82:85], v[66:81]
	s_setprio 0
	s_add_i32 s0, s0, 31
	s_cmp_le_i32 s0, s36
	s_cbranch_scc1 .Lsb1_max
	v_cmp_gt_i32_e64 s[30:31], 26, v217
	v_cmp_gt_i32_e64 s[34:35], 27, v217
	v_cmp_gt_i32_e64 s[28:29], 25, v217
	s_and_b64 s[30:31], s[34:35], s[30:31]
	v_cmp_gt_i32_e64 s[26:27], 24, v217
	s_and_b64 s[28:29], s[30:31], s[28:29]
	v_cmp_gt_i32_e64 s[24:25], 19, v217
	s_and_b64 s[26:27], s[28:29], s[26:27]
	v_cmp_gt_i32_e64 s[22:23], 18, v217
	s_and_b64 s[24:25], s[26:27], s[24:25]
	v_cmp_gt_i32_e64 s[18:19], 17, v217
	s_and_b64 s[22:23], s[24:25], s[22:23]
	v_cmp_gt_i32_e64 s[16:17], 16, v217
	s_and_b64 s[18:19], s[22:23], s[18:19]
	v_cmp_gt_i32_e64 s[14:15], 11, v217
	s_and_b64 s[16:17], s[18:19], s[16:17]
	v_cmp_gt_i32_e64 s[12:13], 10, v217
	s_and_b64 s[14:15], s[16:17], s[14:15]
	v_cmp_gt_i32_e64 s[10:11], 9, v217
	s_and_b64 s[12:13], s[14:15], s[12:13]
	v_cmp_gt_i32_e64 s[8:9], 8, v217
	s_and_b64 s[10:11], s[12:13], s[10:11]
	v_cmp_gt_i32_e64 s[6:7], 3, v217
	s_and_b64 s[8:9], s[10:11], s[8:9]
	v_cmp_gt_i32_e64 s[4:5], 2, v217
	s_and_b64 s[6:7], s[8:9], s[6:7]
	v_cmp_gt_i32_e64 s[0:1], 1, v217
	s_and_b64 s[4:5], s[6:7], s[4:5]
	v_cmp_gt_i32_e32 vcc, 0, v217
	s_and_b64 s[0:1], s[4:5], s[0:1]
	s_and_b64 vcc, s[0:1], vcc
	v_cndmask_b32_e64 v81, v81, v229, s[34:35]
	v_cndmask_b32_e64 v80, v80, v229, s[30:31]
	v_cndmask_b32_e64 v79, v79, v229, s[28:29]
	v_cndmask_b32_e64 v78, v78, v229, s[26:27]
	v_cndmask_b32_e64 v77, v77, v229, s[24:25]
	v_cndmask_b32_e64 v76, v76, v229, s[22:23]
	v_cndmask_b32_e64 v75, v75, v229, s[18:19]
	v_cndmask_b32_e64 v74, v74, v229, s[16:17]
	v_cndmask_b32_e64 v73, v73, v229, s[14:15]
	v_cndmask_b32_e64 v72, v72, v229, s[12:13]
	v_cndmask_b32_e64 v71, v71, v229, s[10:11]
	v_cndmask_b32_e64 v70, v70, v229, s[8:9]
	v_cndmask_b32_e64 v69, v69, v229, s[6:7]
	v_cndmask_b32_e64 v68, v68, v229, s[4:5]
	v_cndmask_b32_e64 v67, v67, v229, s[0:1]
	v_cndmask_b32_e32 v66, v66, v229, vcc

; DI unsigned pk2(float lo, float hi) { f32x2 v = {lo, hi}; return __builtin_bit_cast(unsigned, __builtin_convertvector(v, bf2_t)); }
; #define MFMA32(a, b, c) __builtin_amdgcn_mfma_f32_32x32x16_bf16((a), (b), (c), 0, 0, 0)
; DI void attn_unit(const Params& p, int b, int h, int qb, LAS unsigned char* lds, int tid, int lane, int wave) {
;     ...
;             const float muse = (mrow == -INFINITY) ? 0.f : mrow;
;             float ps = 0.f;
; #pragma unroll
;             for (int j = 0; j < 16; ++j) { s[j] = __builtin_amdgcn_exp2f(s[j] - muse); ps += s[j]; }
;             lrow += ps;
; #pragma unroll
;             for (int ks = 0; ks < 2; ++ks) {
;                 u32x4 pw; pw.x = pk2(s[8 * ks], s[8 * ks + 1]); pw.y = pk2(s[8 * ks + 2], s[8 * ks + 3]); pw.z = pk2(s[8 * ks + 4], s[8 * ks + 5]); pw.w = pk2(s[8 * ks + 6], s[8 * ks + 7]);
;                 const bf16x8 pf = __builtin_bit_cast(bf16x8, pw);
;                 __builtin_amdgcn_s_setprio(1);
; #pragma unroll
;                 for (int blk = 0; blk < 4; ++blk) o[blk] = MFMA32(vf[ks][blk], pf, o[blk]);
;                 __builtin_amdgcn_s_setprio(0);
;             }
;         }
;         if (st + 1 < nst) AT_WRITE(buf ^ 1);
.Lsb1_c2:
	v_exp_f32_e32 v66, v66
	v_exp_f32_e32 v67, v67
	v_exp_f32_e32 v68, v68
	v_exp_f32_e32 v69, v69
	v_exp_f32_e32 v70, v70
	v_exp_f32_e32 v71, v71
	v_exp_f32_e32 v72, v72
	v_exp_f32_e32 v73, v73
	v_exp_f32_e32 v74, v74
	v_exp_f32_e32 v75, v75
	v_exp_f32_e32 v76, v76
	v_exp_f32_e32 v77, v77
	v_exp_f32_e32 v78, v78
	v_exp_f32_e32 v79, v79
	v_exp_f32_e32 v80, v80
	v_exp_f32_e32 v81, v81
	v_pk_add_f32 v[194:195], v[66:67], v[68:69]
	v_pk_add_f32 v[194:195], v[194:195], v[70:71]
	v_pk_add_f32 v[194:195], v[194:195], v[72:73]
	v_pk_add_f32 v[194:195], v[194:195], v[74:75]
	v_pk_add_f32 v[194:195], v[194:195], v[76:77]
	v_pk_add_f32 v[194:195], v[194:195], v[78:79]
	v_pk_add_f32 v[194:195], v[194:195], v[80:81]
	v_add_f32_e32 v194, v194, v195
	v_cvt_pk_bf16_f32 v66, v66, v67
	v_cvt_pk_bf16_f32 v67, v68, v69
	v_cvt_pk_bf16_f32 v68, v70, v71
	v_cvt_pk_bf16_f32 v69, v72, v73
	v_cvt_pk_bf16_f32 v70, v74, v75
	v_cvt_pk_bf16_f32 v71, v76, v77
	v_cvt_pk_bf16_f32 v72, v78, v79
	v_cvt_pk_bf16_f32 v73, v80, v81
	v_add_f32_e32 v203, v203, v194
	s_xor_b32 s0, s78, 1
	s_cmp_eq_u32 s0, 0
	s_cbranch_scc1 .Lsb1_b0
	s_waitcnt vmcnt(3)
	ds_write2_b64 v209, v[130:131], v[132:133] offset1:2
	s_waitcnt vmcnt(2)
	ds_write2_b64 v210, v[134:135], v[136:137] offset1:2
	s_waitcnt vmcnt(1)
	ds_write2_b64 v211, v[138:139], v[140:141] offset1:2
	s_waitcnt vmcnt(0)
	ds_write2_b64 v212, v[142:143], v[144:145] offset1:2
	s_branch .Lsb1_join

; DI unsigned pk2(float lo, float hi) { f32x2 v = {lo, hi}; return __builtin_bit_cast(unsigned, __builtin_convertvector(v, bf2_t)); }
; #define MFMA32(a, b, c) __builtin_amdgcn_mfma_f32_32x32x16_bf16((a), (b), (c), 0, 0, 0)
; DI void attn_unit(const Params& p, int b, int h, int qb, LAS unsigned char* lds, int tid, int lane, int wave) {
;     ...
;             for (int ks = 0; ks < 2; ++ks) {
;                 u32x4 pw; pw.x = pk2(s[8 * ks], s[8 * ks + 1]); pw.y = pk2(s[8 * ks + 2], s[8 * ks + 3]); pw.z = pk2(s[8 * ks + 4], s[8 * ks + 5]); pw.w = pk2(s[8 * ks + 6], s[8 * ks + 7]);
;                 const bf16x8 pf = __builtin_bit_cast(bf16x8, pw);
;                 __builtin_amdgcn_s_setprio(1);
; #pragma unroll
;                 for (int blk = 0; blk < 4; ++blk) o[blk] = MFMA32(vf[ks][blk], pf, o[blk]);
;                 __builtin_amdgcn_s_setprio(0);
;             }
;         }
;         if (st + 1 < nst) AT_WRITE(buf ^ 1);
;         __syncthreads();
.Lsb1_join:
	s_add_u32 s98, s98, 0x18000
	s_addc_u32 s99, s99, 0
	s_add_u32 s100, s100, 0x80
	s_addc_u32 s101, s101, 0
	s_add_i32 s62, s62, 64
	s_add_i32 s63, s63, 1
	v_subrev_u32_e32 v217, 64, v217
	s_cmp_eq_u32 s59, s62
	s_waitcnt lgkmcnt(0)
	s_barrier
	s_cbranch_scc0 .Lsb1_top
	v_mfma_f32_32x32x16_bf16 v[50:65], v[166:169], v[66:69], v[50:65]
	v_mfma_f32_32x32x16_bf16 v[34:49], v[170:173], v[66:69], v[34:49]
	v_mfma_f32_32x32x16_bf16 v[18:33], v[178:181], v[66:69], v[18:33]
	v_mfma_f32_32x32x16_bf16 v[2:17], v[174:177], v[66:69], v[2:17]
	v_mfma_f32_32x32x16_bf16 v[50:65], v[150:153], v[70:73], v[50:65]
	v_mfma_f32_32x32x16_bf16 v[34:49], v[162:165], v[70:73], v[34:49]
	v_mfma_f32_32x32x16_bf16 v[18:33], v[158:161], v[70:73], v[18:33]
	v_mfma_f32_32x32x16_bf16 v[2:17], v[154:157], v[70:73], v[2:17]
	s_setprio 0
	s_branch .LBB0_434
.Lsb1_skipd:
	s_setprio 0
	s_xor_b32 s0, s78, 1
	s_cmp_eq_u32 s0, 0
	s_cbranch_scc1 .Lsb1_sb0
	s_waitcnt vmcnt(3)
	ds_write2_b64 v209, v[130:131], v[132:133] offset1:2
	s_waitcnt vmcnt(2)
	ds_write2_b64 v210, v[134:135], v[136:137] offset1:2
	s_waitcnt vmcnt(1)
	ds_write2_b64 v211, v[138:139], v[140:141] offset1:2
	s_waitcnt vmcnt(0)
	ds_write2_b64 v212, v[142:143], v[144:145] offset1:2
	s_branch .Lsb1_sjoin

; DI unsigned pk2(float lo, float hi) { f32x2 v = {lo, hi}; return __builtin_bit_cast(unsigned, __builtin_convertvector(v, bf2_t)); }
; #define MFMA32(a, b, c) __builtin_amdgcn_mfma_f32_32x32x16_bf16((a), (b), (c), 0, 0, 0)
; DI void attn_unit(const Params& p, int b, int h, int qb, LAS unsigned char* lds, int tid, int lane, int wave) {
;     ...
;             float ps = 0.f;
; #pragma unroll
;             for (int j = 0; j < 16; ++j) { s[j] = __builtin_amdgcn_exp2f(s[j] - muse); ps += s[j]; }
;             lrow += ps;
; #pragma unroll
;             for (int ks = 0; ks < 2; ++ks) {
;                 u32x4 pw; pw.x = pk2(s[8 * ks], s[8 * ks + 1]); pw.y = pk2(s[8 * ks + 2], s[8 * ks + 3]); pw.z = pk2(s[8 * ks + 4], s[8 * ks + 5]); pw.w = pk2(s[8 * ks + 6], s[8 * ks + 7]);
;                 const bf16x8 pf = __builtin_bit_cast(bf16x8, pw);
;                 __builtin_amdgcn_s_setprio(1);
; #pragma unroll
;                 for (int blk = 0; blk < 4; ++blk) o[blk] = MFMA32(vf[ks][blk], pf, o[blk]);
;                 __builtin_amdgcn_s_setprio(0);
;             }
;         }
;         if (st + 1 < nst) AT_WRITE(buf ^ 1);
;         __syncthreads();
.Lsb1_sjoin:
	s_add_u32 s98, s98, 0x18000
	s_addc_u32 s99, s99, 0
	s_add_u32 s100, s100, 0x80
	s_addc_u32 s101, s101, 0
	s_add_i32 s62, s62, 64
	s_add_i32 s63, s63, 1
	v_subrev_u32_e32 v217, 64, v217
	s_cmp_eq_u32 s59, s62
	s_waitcnt lgkmcnt(0)
	s_barrier
	s_cbranch_scc1 .LBB0_434
	global_load_dwordx4 v[130:133], v184, s[100:101]
	global_load_dwordx4 v[134:137], v185, s[100:101]
	global_load_dwordx4 v[138:141], v186, s[100:101]
	global_load_dwordx4 v[142:145], v187, s[100:101]
	s_and_b32 s78, s63, 1
	s_branch .Lsb1_skipd
.LBB0_427:
	v_exp_f32_e32 v66, v66
	v_exp_f32_e32 v67, v67
	v_exp_f32_e32 v68, v68
	v_exp_f32_e32 v69, v69
	v_exp_f32_e32 v70, v70
	v_exp_f32_e32 v71, v71
	v_exp_f32_e32 v72, v72
	v_exp_f32_e32 v73, v73
	v_exp_f32_e32 v74, v74
	v_exp_f32_e32 v75, v75
	v_exp_f32_e32 v76, v76
	v_exp_f32_e32 v77, v77
	v_exp_f32_e32 v78, v78
	v_exp_f32_e32 v79, v79
	v_exp_f32_e32 v80, v80
	v_exp_f32_e32 v81, v81
	v_pk_add_f32 v[194:195], v[66:67], v[68:69]
	v_pk_add_f32 v[194:195], v[194:195], v[70:71]
	v_pk_add_f32 v[194:195], v[194:195], v[72:73]
	v_pk_add_f32 v[194:195], v[194:195], v[74:75]
	v_pk_add_f32 v[194:195], v[194:195], v[76:77]
	v_pk_add_f32 v[194:195], v[194:195], v[78:79]
	v_pk_add_f32 v[194:195], v[194:195], v[80:81]
	v_add_f32_e32 v194, v194, v195
	v_cvt_pk_bf16_f32 v66, v66, v67
	v_cvt_pk_bf16_f32 v67, v68, v69
	v_cvt_pk_bf16_f32 v68, v70, v71
	v_cvt_pk_bf16_f32 v69, v72, v73
	s_setprio 0
	s_waitcnt lgkmcnt(7)
	v_mfma_f32_32x32x16_bf16 v[50:65], v[166:169], v[66:69], v[50:65]
	s_waitcnt lgkmcnt(5)
	v_mfma_f32_32x32x16_bf16 v[34:49], v[170:173], v[66:69], v[34:49]
	s_waitcnt lgkmcnt(4)
	v_mfma_f32_32x32x16_bf16 v[18:33], v[178:181], v[66:69], v[18:33]
	s_waitcnt lgkmcnt(3)
	v_mfma_f32_32x32x16_bf16 v[2:17], v[174:177], v[66:69], v[2:17]
	s_setprio 0
	v_cvt_pk_bf16_f32 v66, v74, v75
	v_cvt_pk_bf16_f32 v67, v76, v77
	v_cvt_pk_bf16_f32 v68, v78, v79
	v_cvt_pk_bf16_f32 v69, v80, v81
	s_setprio 0
	s_nop 0
	v_mfma_f32_32x32x16_bf16 v[50:65], v[150:153], v[66:69], v[50:65]
	s_waitcnt lgkmcnt(2)
	v_mfma_f32_32x32x16_bf16 v[34:49], v[162:165], v[66:69], v[34:49]
	s_waitcnt lgkmcnt(1)
	v_mfma_f32_32x32x16_bf16 v[18:33], v[158:161], v[66:69], v[18:33]
	s_waitcnt lgkmcnt(0)
	v_mfma_f32_32x32x16_bf16 v[2:17], v[154:157], v[66:69], v[2:17]
	s_setprio 0
	v_add_f32_e32 v203, v203, v194

; #define LAS __attribute__((address_space(3)))
; #define MFMA32(a, b, c) __builtin_amdgcn_mfma_f32_32x32x16_bf16((a), (b), (c), 0, 0, 0)
; DI void attn_unit(const Params& p, int b, int h, int qb, LAS unsigned char* lds, int tid, int lane, int wave) {
;     ...
;         const int kb = st * 64 + g * 32;
;         if (kb <= qr0 + 31) {
;             f32x16 s;
; #pragma unroll
;             for (int j = 0; j < 16; ++j) s[j] = 0.f;
;             const LAS unsigned char* kp = lds + AT_K0 + buf * AT_KB + (g * 32 + r) * 400 + hh * 16;
;             bf16x8 kf[12];
; #pragma unroll
;             for (int kk = 0; kk < 12; ++kk) kf[kk] = *(const LAS bf16x8*)(kp + kk * 32);
;             __builtin_amdgcn_sched_barrier(0);
;             __builtin_amdgcn_s_setprio(1);
; #pragma unroll
;             for (int kk = 0; kk < 12; ++kk) s = MFMA32(kf[kk], qf[kk], s);
;             __builtin_amdgcn_s_setprio(0);
;             const LAS unsigned char* vp = lds + AT_V0 + buf * AT_VB + r * 136 + (g * 32 + 4 * hh) * 2;
;             bf16x8 vf[2][4];
; #pragma unroll
;             for (int ks = 0; ks < 2; ++ks)
; #pragma unroll
;                 for (int blk = 0; blk < 4; ++blk) {
;                     const s16x4 lo = *(const LAS s16x4*)(vp + blk * 32 * 136 + ks * 32), hi = *(const LAS s16x4*)(vp + blk * 32 * 136 + ks * 32 + 16);
;                     vf[ks][blk] = __builtin_shufflevector(lo, hi, 0, 1, 2, 3, 4, 5, 6, 7);
;                 }
;             __builtin_amdgcn_sched_barrier(0);
;             if (kb + 31 > qr0) {
;                 const int qa = qr0 + r - kb - 4 * hh;
; #pragma unroll
;                 for (int j = 0; j < 16; ++j) if ((j & 3) + 8 * (j >> 2) > qa) s[j] = -INFINITY;
.Lt1_nb:
	s_and_b32 s78, s63, 1
	s_add_i32 s0, s56, s62
	s_cmp_gt_i32 s0, s57
	s_cbranch_scc1 .LBB0_428
	s_mul_i32 s1, s78, 0x6400
	v_add_u32_e32 v0, s1, v216
	ds_read_b128 v[66:69], v0
	ds_read_b128 v[150:153], v0 offset:32
	ds_read_b128 v[154:157], v0 offset:64
	ds_read_b128 v[158:161], v0 offset:96
	ds_read_b128 v[162:165], v0 offset:128
	ds_read_b128 v[166:169], v0 offset:160
	ds_read_b128 v[170:173], v0 offset:192
	ds_read_b128 v[174:177], v0 offset:224
	ds_read_b128 v[178:181], v0 offset:256
	ds_read_b128 v[194:197], v0 offset:288
	ds_read_b128 v[198:201], v0 offset:320
	ds_read_b128 v[218:221], v0 offset:352
	s_setprio 1
	s_waitcnt lgkmcnt(11)
	v_mfma_f32_32x32x16_bf16 v[66:81], v[66:69], v[126:129], v[230:245]
	s_mul_i32 s1, s78, 0x4800
	v_add_u32_e32 v0, s1, v206
	s_waitcnt lgkmcnt(10)
	v_mfma_f32_32x32x16_bf16 v[66:81], v[150:153], v[122:125], v[66:81]
	s_waitcnt lgkmcnt(9)
	v_mfma_f32_32x32x16_bf16 v[66:81], v[154:157], v[118:121], v[66:81]
	s_waitcnt lgkmcnt(8)
	v_mfma_f32_32x32x16_bf16 v[66:81], v[158:161], v[114:117], v[66:81]
	s_waitcnt lgkmcnt(7)
	v_mfma_f32_32x32x16_bf16 v[66:81], v[162:165], v[110:113], v[66:81]
	s_waitcnt lgkmcnt(6)
	v_mfma_f32_32x32x16_bf16 v[66:81], v[166:169], v[106:109], v[66:81]
	ds_read_b128 v[166:169], v0 offset:51200
	ds_read_b128 v[150:153], v0 offset:51232
	s_waitcnt lgkmcnt(7)
	v_mfma_f32_32x32x16_bf16 v[66:81], v[170:173], v[102:105], v[66:81]
	ds_read_b128 v[170:173], v0 offset:55808
	s_waitcnt lgkmcnt(7)
	v_mfma_f32_32x32x16_bf16 v[66:81], v[174:177], v[98:101], v[66:81]
	s_waitcnt lgkmcnt(6)
	v_mfma_f32_32x32x16_bf16 v[66:81], v[178:181], v[94:97], v[66:81]
	ds_read_b128 v[178:181], v0 offset:60416
	ds_read_b128 v[174:177], v0 offset:65024
	ds_read_b128 v[162:165], v0 offset:55840
	ds_read_b128 v[158:161], v0 offset:60448
	ds_read_b128 v[154:157], v0 offset:65056
	s_waitcnt lgkmcnt(10)
	v_mfma_f32_32x32x16_bf16 v[66:81], v[194:197], v[90:93], v[66:81]
	s_waitcnt lgkmcnt(9)
	v_mfma_f32_32x32x16_bf16 v[66:81], v[198:201], v[86:89], v[66:81]
	s_waitcnt lgkmcnt(8)
	v_mfma_f32_32x32x16_bf16 v[66:81], v[218:221], v[82:85], v[66:81]
	s_setprio 0
	s_add_i32 s0, s0, 31
	s_cmp_le_i32 s0, s36
	s_cbranch_scc1 .LBB0_432
	v_cmp_gt_i32_e64 s[30:31], 26, v217
	v_cmp_gt_i32_e64 s[34:35], 27, v217
	v_cmp_gt_i32_e64 s[28:29], 25, v217
	s_and_b64 s[30:31], s[34:35], s[30:31]
	v_cmp_gt_i32_e64 s[26:27], 24, v217
	s_and_b64 s[28:29], s[30:31], s[28:29]
	v_cmp_gt_i32_e64 s[24:25], 19, v217
	s_and_b64 s[26:27], s[28:29], s[26:27]
	v_cmp_gt_i32_e64 s[22:23], 18, v217
	s_and_b64 s[24:25], s[26:27], s[24:25]
	v_cmp_gt_i32_e64 s[18:19], 17, v217
	s_and_b64 s[22:23], s[24:25], s[22:23]
	v_cmp_gt_i32_e64 s[16:17], 16, v217
	s_and_b64 s[18:19], s[22:23], s[18:19]
	v_cmp_gt_i32_e64 s[14:15], 11, v217
	s_and_b64 s[16:17], s[18:19], s[16:17]
	v_cmp_gt_i32_e64 s[12:13], 10, v217
	s_and_b64 s[14:15], s[16:17], s[14:15]
	v_cmp_gt_i32_e64 s[10:11], 9, v217
	s_and_b64 s[12:13], s[14:15], s[12:13]
	v_cmp_gt_i32_e64 s[8:9], 8, v217
	s_and_b64 s[10:11], s[12:13], s[10:11]
	v_cmp_gt_i32_e64 s[6:7], 3, v217
	s_and_b64 s[8:9], s[10:11], s[8:9]
	v_cmp_gt_i32_e64 s[4:5], 2, v217
	s_and_b64 s[6:7], s[8:9], s[6:7]
	v_cmp_gt_i32_e64 s[0:1], 1, v217
	s_and_b64 s[4:5], s[6:7], s[4:5]
	v_cmp_gt_i32_e32 vcc, 0, v217
	s_and_b64 s[0:1], s[4:5], s[0:1]
	s_and_b64 vcc, s[0:1], vcc
	v_cndmask_b32_e64 v81, v81, v229, s[34:35]
	v_cndmask_b32_e64 v80, v80, v229, s[30:31]
	v_cndmask_b32_e64 v79, v79, v229, s[28:29]
	v_cndmask_b32_e64 v78, v78, v229, s[26:27]
	v_cndmask_b32_e64 v77, v77, v229, s[24:25]
	v_cndmask_b32_e64 v76, v76, v229, s[22:23]
	v_cndmask_b32_e64 v75, v75, v229, s[18:19]
	v_cndmask_b32_e64 v74, v74, v229, s[16:17]
	v_cndmask_b32_e64 v73, v73, v229, s[14:15]
	v_cndmask_b32_e64 v72, v72, v229, s[12:13]
	v_cndmask_b32_e64 v71, v71, v229, s[10:11]
	v_cndmask_b32_e64 v70, v70, v229, s[8:9]
	v_cndmask_b32_e64 v69, v69, v229, s[6:7]
	v_cndmask_b32_e64 v68, v68, v229, s[4:5]
	v_cndmask_b32_e64 v67, v67, v229, s[0:1]
	v_cndmask_b32_e32 v66, v66, v229, vcc

; #define LAS __attribute__((address_space(3)))
; #define MFMA32(a, b, c) __builtin_amdgcn_mfma_f32_32x32x16_bf16((a), (b), (c), 0, 0, 0)
; #define AT_LOAD(st) do { _Pragma("unroll") for (int e = 0; e < 3; ++e) pk[e] = *(const u32x4*)(kbase + (size_t)((st) * 64 + krow[e]) * 768 + kcol[e] * 8); \
;         _Pragma("unroll") for (int e = 0; e < 2; ++e) { const int c = tid + 512 * e; pv[e] = *(const u32x4*)(vbase + (size_t)(c >> 3) * SEQ + (st) * 64 + (c & 7) * 8); } } while (0)
; DI void attn_unit(const Params& p, int b, int h, int qb, LAS unsigned char* lds, int tid, int lane, int wave) {
;     ...
;     for (int st = 0; st < nst; ++st) {
;         const int buf = st & 1;
;         if (st + 1 < nst) AT_LOAD(st + 1);
;         const int kb = st * 64 + g * 32;
;         if (kb <= qr0 + 31) {
;             f32x16 s;
; #pragma unroll
;             for (int j = 0; j < 16; ++j) s[j] = 0.f;
;             const LAS unsigned char* kp = lds + AT_K0 + buf * AT_KB + (g * 32 + r) * 400 + hh * 16;
;             bf16x8 kf[12];
; #pragma unroll
;             for (int kk = 0; kk < 12; ++kk) kf[kk] = *(const LAS bf16x8*)(kp + kk * 32);
;             __builtin_amdgcn_sched_barrier(0);
;             __builtin_amdgcn_s_setprio(1);
; #pragma unroll
;             for (int kk = 0; kk < 12; ++kk) s = MFMA32(kf[kk], qf[kk], s);
;             __builtin_amdgcn_s_setprio(0);
;             const LAS unsigned char* vp = lds + AT_V0 + buf * AT_VB + r * 136 + (g * 32 + 4 * hh) * 2;
;             bf16x8 vf[2][4];
; #pragma unroll
;             for (int ks = 0; ks < 2; ++ks)
; #pragma unroll
;                 for (int blk = 0; blk < 4; ++blk) {
;                     const s16x4 lo = *(const LAS s16x4*)(vp + blk * 32 * 136 + ks * 32), hi = *(const LAS s16x4*)(vp + blk * 32 * 136 + ks * 32 + 16);
;                     vf[ks][blk] = __builtin_shufflevector(lo, hi, 0, 1, 2, 3, 4, 5, 6, 7);
;                 }
;             __builtin_amdgcn_sched_barrier(0);
;             if (kb + 31 > qr0) {
;                 const int qa = qr0 + r - kb - 4 * hh;
; #pragma unroll
;                 for (int j = 0; j < 16; ++j) if ((j & 3) + 8 * (j >> 2) > qa) s[j] = -INFINITY;
.Lsb2_first:
	s_setprio 1
	global_load_dwordx4 v[130:133], v184, s[100:101]
	global_load_dwordx4 v[134:137], v185, s[100:101]
	global_load_dwordx4 v[138:141], v186, s[100:101]
	global_load_dwordx4 v[142:145], v187, s[100:101]
	s_and_b32 s57, s55, 1
	s_add_i32 s0, s53, s54
	s_cmp_gt_i32 s0, s56
	s_cbranch_scc1 .Lsb2_skipd
	s_branch .Lsb2_qk
.Lsb2_top:
	s_setprio 1
	v_mfma_f32_32x32x16_bf16 v[50:65], v[166:169], v[66:69], v[50:65]
	v_mfma_f32_32x32x16_bf16 v[34:49], v[170:173], v[66:69], v[34:49]
	v_mfma_f32_32x32x16_bf16 v[18:33], v[178:181], v[66:69], v[18:33]
	v_mfma_f32_32x32x16_bf16 v[2:17], v[174:177], v[66:69], v[2:17]
	v_mfma_f32_32x32x16_bf16 v[50:65], v[150:153], v[70:73], v[50:65]
	v_mfma_f32_32x32x16_bf16 v[34:49], v[162:165], v[70:73], v[34:49]
	v_mfma_f32_32x32x16_bf16 v[18:33], v[158:161], v[70:73], v[18:33]
	v_mfma_f32_32x32x16_bf16 v[2:17], v[154:157], v[70:73], v[2:17]
	global_load_dwordx4 v[130:133], v184, s[100:101]
	global_load_dwordx4 v[134:137], v185, s[100:101]
	global_load_dwordx4 v[138:141], v186, s[100:101]
	global_load_dwordx4 v[142:145], v187, s[100:101]
	s_and_b32 s57, s55, 1
	s_add_i32 s0, s53, s54
	s_cmp_gt_i32 s0, s56
	s_cbranch_scc1 .Lsb2_skipd
.Lsb2_qk:
	s_mul_i32 s1, s57, 0x6400
	v_add_u32_e32 v0, s1, v216
	ds_read_b128 v[66:69], v0
	ds_read_b128 v[150:153], v0 offset:32
	ds_read_b128 v[154:157], v0 offset:64
	ds_read_b128 v[158:161], v0 offset:96
	ds_read_b128 v[162:165], v0 offset:128
	ds_read_b128 v[166:169], v0 offset:160
	ds_read_b128 v[170:173], v0 offset:192
	ds_read_b128 v[174:177], v0 offset:224
	ds_read_b128 v[178:181], v0 offset:256
	ds_read_b128 v[194:197], v0 offset:288
	ds_read_b128 v[198:201], v0 offset:320
	ds_read_b128 v[218:221], v0 offset:352
	s_waitcnt lgkmcnt(11)
	v_mfma_f32_32x32x16_bf16 v[66:81], v[66:69], v[126:129], v[230:245]
	s_mul_i32 s1, s57, 0x4800
	v_add_u32_e32 v0, s1, v206
	s_waitcnt lgkmcnt(10)
	v_mfma_f32_32x32x16_bf16 v[66:81], v[150:153], v[122:125], v[66:81]
	s_waitcnt lgkmcnt(9)
	v_mfma_f32_32x32x16_bf16 v[66:81], v[154:157], v[118:121], v[66:81]
	s_waitcnt lgkmcnt(8)
	v_mfma_f32_32x32x16_bf16 v[66:81], v[158:161], v[114:117], v[66:81]
	s_waitcnt lgkmcnt(7)
	v_mfma_f32_32x32x16_bf16 v[66:81], v[162:165], v[110:113], v[66:81]
	s_waitcnt lgkmcnt(6)
	v_mfma_f32_32x32x16_bf16 v[66:81], v[166:169], v[106:109], v[66:81]
	ds_read_b128 v[166:169], v0 offset:51200
	ds_read_b128 v[150:153], v0 offset:51232
	s_waitcnt lgkmcnt(7)
	v_mfma_f32_32x32x16_bf16 v[66:81], v[170:173], v[102:105], v[66:81]
	ds_read_b128 v[170:173], v0 offset:55808
	s_waitcnt lgkmcnt(7)
	v_mfma_f32_32x32x16_bf16 v[66:81], v[174:177], v[98:101], v[66:81]
	s_waitcnt lgkmcnt(6)
	v_mfma_f32_32x32x16_bf16 v[66:81], v[178:181], v[94:97], v[66:81]
	ds_read_b128 v[178:181], v0 offset:60416
	ds_read_b128 v[174:177], v0 offset:65024
	ds_read_b128 v[162:165], v0 offset:55840
	ds_read_b128 v[158:161], v0 offset:60448
	ds_read_b128 v[154:157], v0 offset:65056
	s_waitcnt lgkmcnt(10)
	v_mfma_f32_32x32x16_bf16 v[66:81], v[194:197], v[90:93], v[66:81]
	s_waitcnt lgkmcnt(9)
	v_mfma_f32_32x32x16_bf16 v[66:81], v[198:201], v[86:89], v[66:81]
	s_waitcnt lgkmcnt(8)
	v_mfma_f32_32x32x16_bf16 v[66:81], v[218:221], v[82:85], v[66:81]
	s_setprio 0
	s_add_i32 s0, s0, 31
	s_cmp_le_i32 s0, s36
	s_cbranch_scc1 .Lsb2_max
	v_cmp_gt_i32_e64 s[30:31], 26, v217
	v_cmp_gt_i32_e64 s[34:35], 27, v217
	v_cmp_gt_i32_e64 s[28:29], 25, v217
	s_and_b64 s[30:31], s[34:35], s[30:31]
	v_cmp_gt_i32_e64 s[26:27], 24, v217
	s_and_b64 s[28:29], s[30:31], s[28:29]
	v_cmp_gt_i32_e64 s[24:25], 19, v217
	s_and_b64 s[26:27], s[28:29], s[26:27]
	v_cmp_gt_i32_e64 s[22:23], 18, v217
	s_and_b64 s[24:25], s[26:27], s[24:25]
	v_cmp_gt_i32_e64 s[18:19], 17, v217
	s_and_b64 s[22:23], s[24:25], s[22:23]
	v_cmp_gt_i32_e64 s[16:17], 16, v217
	s_and_b64 s[18:19], s[22:23], s[18:19]
	v_cmp_gt_i32_e64 s[14:15], 11, v217
	s_and_b64 s[16:17], s[18:19], s[16:17]
	v_cmp_gt_i32_e64 s[12:13], 10, v217
	s_and_b64 s[14:15], s[16:17], s[14:15]
	v_cmp_gt_i32_e64 s[10:11], 9, v217
	s_and_b64 s[12:13], s[14:15], s[12:13]
	v_cmp_gt_i32_e64 s[8:9], 8, v217
	s_and_b64 s[10:11], s[12:13], s[10:11]
	v_cmp_gt_i32_e64 s[6:7], 3, v217
	s_and_b64 s[8:9], s[10:11], s[8:9]
	v_cmp_gt_i32_e64 s[4:5], 2, v217
	s_and_b64 s[6:7], s[8:9], s[6:7]
	v_cmp_gt_i32_e64 s[0:1], 1, v217
	s_and_b64 s[4:5], s[6:7], s[4:5]
	v_cmp_gt_i32_e32 vcc, 0, v217
	s_and_b64 s[0:1], s[4:5], s[0:1]
	s_and_b64 vcc, s[0:1], vcc
	v_cndmask_b32_e64 v81, v81, v229, s[34:35]
	v_cndmask_b32_e64 v80, v80, v229, s[30:31]
	v_cndmask_b32_e64 v79, v79, v229, s[28:29]
	v_cndmask_b32_e64 v78, v78, v229, s[26:27]
	v_cndmask_b32_e64 v77, v77, v229, s[24:25]
	v_cndmask_b32_e64 v76, v76, v229, s[22:23]
	v_cndmask_b32_e64 v75, v75, v229, s[18:19]
	v_cndmask_b32_e64 v74, v74, v229, s[16:17]
	v_cndmask_b32_e64 v73, v73, v229, s[14:15]
	v_cndmask_b32_e64 v72, v72, v229, s[12:13]
	v_cndmask_b32_e64 v71, v71, v229, s[10:11]
	v_cndmask_b32_e64 v70, v70, v229, s[8:9]
	v_cndmask_b32_e64 v69, v69, v229, s[6:7]
	v_cndmask_b32_e64 v68, v68, v229, s[4:5]
	v_cndmask_b32_e64 v67, v67, v229, s[0:1]
	v_cndmask_b32_e32 v66, v66, v229, vcc

; DI unsigned pk2(float lo, float hi) { f32x2 v = {lo, hi}; return __builtin_bit_cast(unsigned, __builtin_convertvector(v, bf2_t)); }
; #define MFMA32(a, b, c) __builtin_amdgcn_mfma_f32_32x32x16_bf16((a), (b), (c), 0, 0, 0)
; DI void attn_unit(const Params& p, int b, int h, int qb, LAS unsigned char* lds, int tid, int lane, int wave) {
;     ...
;             const float muse = (mrow == -INFINITY) ? 0.f : mrow;
;             float ps = 0.f;
; #pragma unroll
;             for (int j = 0; j < 16; ++j) { s[j] = __builtin_amdgcn_exp2f(s[j] - muse); ps += s[j]; }
;             lrow += ps;
; #pragma unroll
;             for (int ks = 0; ks < 2; ++ks) {
;                 u32x4 pw; pw.x = pk2(s[8 * ks], s[8 * ks + 1]); pw.y = pk2(s[8 * ks + 2], s[8 * ks + 3]); pw.z = pk2(s[8 * ks + 4], s[8 * ks + 5]); pw.w = pk2(s[8 * ks + 6], s[8 * ks + 7]);
;                 const bf16x8 pf = __builtin_bit_cast(bf16x8, pw);
;                 __builtin_amdgcn_s_setprio(1);
; #pragma unroll
;                 for (int blk = 0; blk < 4; ++blk) o[blk] = MFMA32(vf[ks][blk], pf, o[blk]);
;                 __builtin_amdgcn_s_setprio(0);
;             }
;         }
;         if (st + 1 < nst) AT_WRITE(buf ^ 1);
.Lsb2_c2:
	v_exp_f32_e32 v66, v66
	v_exp_f32_e32 v67, v67
	v_exp_f32_e32 v68, v68
	v_exp_f32_e32 v69, v69
	v_exp_f32_e32 v70, v70
	v_exp_f32_e32 v71, v71
	v_exp_f32_e32 v72, v72
	v_exp_f32_e32 v73, v73
	v_exp_f32_e32 v74, v74
	v_exp_f32_e32 v75, v75
	v_exp_f32_e32 v76, v76
	v_exp_f32_e32 v77, v77
	v_exp_f32_e32 v78, v78
	v_exp_f32_e32 v79, v79
	v_exp_f32_e32 v80, v80
	v_exp_f32_e32 v81, v81
	v_pk_add_f32 v[194:195], v[66:67], v[68:69]
	v_pk_add_f32 v[194:195], v[194:195], v[70:71]
	v_pk_add_f32 v[194:195], v[194:195], v[72:73]
	v_pk_add_f32 v[194:195], v[194:195], v[74:75]
	v_pk_add_f32 v[194:195], v[194:195], v[76:77]
	v_pk_add_f32 v[194:195], v[194:195], v[78:79]
	v_pk_add_f32 v[194:195], v[194:195], v[80:81]
	v_add_f32_e32 v194, v194, v195
	v_cvt_pk_bf16_f32 v66, v66, v67
	v_cvt_pk_bf16_f32 v67, v68, v69
	v_cvt_pk_bf16_f32 v68, v70, v71
	v_cvt_pk_bf16_f32 v69, v72, v73
	v_cvt_pk_bf16_f32 v70, v74, v75
	v_cvt_pk_bf16_f32 v71, v76, v77
	v_cvt_pk_bf16_f32 v72, v78, v79
	v_cvt_pk_bf16_f32 v73, v80, v81
	v_add_f32_e32 v203, v203, v194
	s_xor_b32 s0, s57, 1
	s_cmp_eq_u32 s0, 0
	s_cbranch_scc1 .Lsb2_b0
	s_waitcnt vmcnt(3)
	ds_write2_b64 v209, v[130:131], v[132:133] offset1:2
	s_waitcnt vmcnt(2)
	ds_write2_b64 v210, v[134:135], v[136:137] offset1:2
	s_waitcnt vmcnt(1)
	ds_write2_b64 v211, v[138:139], v[140:141] offset1:2
	s_waitcnt vmcnt(0)
	ds_write2_b64 v212, v[142:143], v[144:145] offset1:2
	s_branch .Lsb2_join

; DI unsigned pk2(float lo, float hi) { f32x2 v = {lo, hi}; return __builtin_bit_cast(unsigned, __builtin_convertvector(v, bf2_t)); }
; #define MFMA32(a, b, c) __builtin_amdgcn_mfma_f32_32x32x16_bf16((a), (b), (c), 0, 0, 0)
; DI void attn_unit(const Params& p, int b, int h, int qb, LAS unsigned char* lds, int tid, int lane, int wave) {
;     ...
;             for (int ks = 0; ks < 2; ++ks) {
;                 u32x4 pw; pw.x = pk2(s[8 * ks], s[8 * ks + 1]); pw.y = pk2(s[8 * ks + 2], s[8 * ks + 3]); pw.z = pk2(s[8 * ks + 4], s[8 * ks + 5]); pw.w = pk2(s[8 * ks + 6], s[8 * ks + 7]);
;                 const bf16x8 pf = __builtin_bit_cast(bf16x8, pw);
;                 __builtin_amdgcn_s_setprio(1);
; #pragma unroll
;                 for (int blk = 0; blk < 4; ++blk) o[blk] = MFMA32(vf[ks][blk], pf, o[blk]);
;                 __builtin_amdgcn_s_setprio(0);
;             }
;         }
;         if (st + 1 < nst) AT_WRITE(buf ^ 1);
;         __syncthreads();
.Lsb2_join:
	s_add_u32 s98, s98, 0x18000
	s_addc_u32 s99, s99, 0
	s_add_u32 s100, s100, 0x80
	s_addc_u32 s101, s101, 0
	s_add_i32 s54, s54, 64
	s_add_i32 s55, s55, 1
	v_subrev_u32_e32 v217, 64, v217
	s_cmp_eq_u32 s52, s54
	s_waitcnt lgkmcnt(0)
	s_barrier
	s_cbranch_scc0 .Lsb2_top
	v_mfma_f32_32x32x16_bf16 v[50:65], v[166:169], v[66:69], v[50:65]
	v_mfma_f32_32x32x16_bf16 v[34:49], v[170:173], v[66:69], v[34:49]
	v_mfma_f32_32x32x16_bf16 v[18:33], v[178:181], v[66:69], v[18:33]
	v_mfma_f32_32x32x16_bf16 v[2:17], v[174:177], v[66:69], v[2:17]
	v_mfma_f32_32x32x16_bf16 v[50:65], v[150:153], v[70:73], v[50:65]
	v_mfma_f32_32x32x16_bf16 v[34:49], v[162:165], v[70:73], v[34:49]
	v_mfma_f32_32x32x16_bf16 v[18:33], v[158:161], v[70:73], v[18:33]
	v_mfma_f32_32x32x16_bf16 v[2:17], v[154:157], v[70:73], v[2:17]
	s_setprio 0
	s_branch .LBB0_452
.Lsb2_skipd:
	s_setprio 0
	s_xor_b32 s0, s57, 1
	s_cmp_eq_u32 s0, 0
	s_cbranch_scc1 .Lsb2_sb0
	s_waitcnt vmcnt(3)
	ds_write2_b64 v209, v[130:131], v[132:133] offset1:2
	s_waitcnt vmcnt(2)
	ds_write2_b64 v210, v[134:135], v[136:137] offset1:2
	s_waitcnt vmcnt(1)
	ds_write2_b64 v211, v[138:139], v[140:141] offset1:2
	s_waitcnt vmcnt(0)
	ds_write2_b64 v212, v[142:143], v[144:145] offset1:2
	s_branch .Lsb2_sjoin

; #define AT_LOAD(st) do { _Pragma("unroll") for (int e = 0; e < 3; ++e) pk[e] = *(const u32x4*)(kbase + (size_t)((st) * 64 + krow[e]) * 768 + kcol[e] * 8); \
;         _Pragma("unroll") for (int e = 0; e < 2; ++e) { const int c = tid + 512 * e; pv[e] = *(const u32x4*)(vbase + (size_t)(c >> 3) * SEQ + (st) * 64 + (c & 7) * 8); } } while (0)
; DI void attn_unit(const Params& p, int b, int h, int qb, LAS unsigned char* lds, int tid, int lane, int wave) {
;     ...
;     for (int st = 0; st < nst; ++st) {
;         const int buf = st & 1;
;         if (st + 1 < nst) AT_LOAD(st + 1);
;     ...
;         if (st + 1 < nst) AT_WRITE(buf ^ 1);
;         __syncthreads();
.Lsb2_sjoin:
	s_add_u32 s98, s98, 0x18000
	s_addc_u32 s99, s99, 0
	s_add_u32 s100, s100, 0x80
	s_addc_u32 s101, s101, 0
	s_add_i32 s54, s54, 64
	s_add_i32 s55, s55, 1
	v_subrev_u32_e32 v217, 64, v217
	s_cmp_eq_u32 s52, s54
	s_waitcnt lgkmcnt(0)
	s_barrier
	s_cbranch_scc1 .LBB0_452
	global_load_dwordx4 v[130:133], v184, s[100:101]
	global_load_dwordx4 v[134:137], v185, s[100:101]
	global_load_dwordx4 v[138:141], v186, s[100:101]
	global_load_dwordx4 v[142:145], v187, s[100:101]
	s_and_b32 s57, s55, 1
	s_branch .Lsb2_skipd

; #define LAS __attribute__((address_space(3)))
; #define MFMA32(a, b, c) __builtin_amdgcn_mfma_f32_32x32x16_bf16((a), (b), (c), 0, 0, 0)
; DI void attn_unit(const Params& p, int b, int h, int qb, LAS unsigned char* lds, int tid, int lane, int wave) {
;     ...
;         const int kb = st * 64 + g * 32;
;         if (kb <= qr0 + 31) {
;             f32x16 s;
; #pragma unroll
;             for (int j = 0; j < 16; ++j) s[j] = 0.f;
;             const LAS unsigned char* kp = lds + AT_K0 + buf * AT_KB + (g * 32 + r) * 400 + hh * 16;
;             bf16x8 kf[12];
; #pragma unroll
;             for (int kk = 0; kk < 12; ++kk) kf[kk] = *(const LAS bf16x8*)(kp + kk * 32);
;             __builtin_amdgcn_sched_barrier(0);
;             __builtin_amdgcn_s_setprio(1);
; #pragma unroll
;             for (int kk = 0; kk < 12; ++kk) s = MFMA32(kf[kk], qf[kk], s);
;             __builtin_amdgcn_s_setprio(0);
;             const LAS unsigned char* vp = lds + AT_V0 + buf * AT_VB + r * 136 + (g * 32 + 4 * hh) * 2;
;             bf16x8 vf[2][4];
; #pragma unroll
;             for (int ks = 0; ks < 2; ++ks)
; #pragma unroll
;                 for (int blk = 0; blk < 4; ++blk) {
;                     const s16x4 lo = *(const LAS s16x4*)(vp + blk * 32 * 136 + ks * 32), hi = *(const LAS s16x4*)(vp + blk * 32 * 136 + ks * 32 + 16);
;                     vf[ks][blk] = __builtin_shufflevector(lo, hi, 0, 1, 2, 3, 4, 5, 6, 7);
;                 }
;             __builtin_amdgcn_sched_barrier(0);
;             if (kb + 31 > qr0) {
;                 const int qa = qr0 + r - kb - 4 * hh;
; #pragma unroll
;                 for (int j = 0; j < 16; ++j) if ((j & 3) + 8 * (j >> 2) > qa) s[j] = -INFINITY;
.Lt2_nb:
	s_and_b32 s57, s55, 1
	s_add_i32 s0, s53, s54
	s_cmp_gt_i32 s0, s56
	s_cbranch_scc1 .LBB0_446
	s_mul_i32 s1, s57, 0x6400
	v_add_u32_e32 v0, s1, v216
	ds_read_b128 v[66:69], v0
	ds_read_b128 v[150:153], v0 offset:32
	ds_read_b128 v[154:157], v0 offset:64
	ds_read_b128 v[158:161], v0 offset:96
	ds_read_b128 v[162:165], v0 offset:128
	ds_read_b128 v[166:169], v0 offset:160
	ds_read_b128 v[170:173], v0 offset:192
	ds_read_b128 v[174:177], v0 offset:224
	ds_read_b128 v[178:181], v0 offset:256
	ds_read_b128 v[194:197], v0 offset:288
	ds_read_b128 v[198:201], v0 offset:320
	ds_read_b128 v[218:221], v0 offset:352
	s_setprio 1
	s_waitcnt lgkmcnt(11)
	v_mfma_f32_32x32x16_bf16 v[66:81], v[66:69], v[126:129], v[230:245]
	s_mul_i32 s1, s57, 0x4800
	v_add_u32_e32 v0, s1, v206
	s_waitcnt lgkmcnt(10)
	v_mfma_f32_32x32x16_bf16 v[66:81], v[150:153], v[122:125], v[66:81]
	s_waitcnt lgkmcnt(9)
	v_mfma_f32_32x32x16_bf16 v[66:81], v[154:157], v[118:121], v[66:81]
	s_waitcnt lgkmcnt(8)
	v_mfma_f32_32x32x16_bf16 v[66:81], v[158:161], v[114:117], v[66:81]
	s_waitcnt lgkmcnt(7)
	v_mfma_f32_32x32x16_bf16 v[66:81], v[162:165], v[110:113], v[66:81]
	s_waitcnt lgkmcnt(6)
	v_mfma_f32_32x32x16_bf16 v[66:81], v[166:169], v[106:109], v[66:81]
	ds_read_b128 v[166:169], v0 offset:51200
	ds_read_b128 v[150:153], v0 offset:51232
	s_waitcnt lgkmcnt(7)
	v_mfma_f32_32x32x16_bf16 v[66:81], v[170:173], v[102:105], v[66:81]
	ds_read_b128 v[170:173], v0 offset:55808
	s_waitcnt lgkmcnt(7)
	v_mfma_f32_32x32x16_bf16 v[66:81], v[174:177], v[98:101], v[66:81]
	s_waitcnt lgkmcnt(6)
	v_mfma_f32_32x32x16_bf16 v[66:81], v[178:181], v[94:97], v[66:81]
	ds_read_b128 v[178:181], v0 offset:60416
	ds_read_b128 v[174:177], v0 offset:65024
	ds_read_b128 v[162:165], v0 offset:55840
	ds_read_b128 v[158:161], v0 offset:60448
	ds_read_b128 v[154:157], v0 offset:65056
	s_waitcnt lgkmcnt(10)
	v_mfma_f32_32x32x16_bf16 v[66:81], v[194:197], v[90:93], v[66:81]
	s_waitcnt lgkmcnt(9)
	v_mfma_f32_32x32x16_bf16 v[66:81], v[198:201], v[86:89], v[66:81]
	s_waitcnt lgkmcnt(8)
	v_mfma_f32_32x32x16_bf16 v[66:81], v[218:221], v[82:85], v[66:81]
	s_setprio 0
	s_add_i32 s0, s0, 31
	s_cmp_le_i32 s0, s36
	s_cbranch_scc1 .LBB0_450
	v_cmp_gt_i32_e64 s[30:31], 26, v217
	v_cmp_gt_i32_e64 s[34:35], 27, v217
	v_cmp_gt_i32_e64 s[28:29], 25, v217
	s_and_b64 s[30:31], s[34:35], s[30:31]
	v_cmp_gt_i32_e64 s[26:27], 24, v217
	s_and_b64 s[28:29], s[30:31], s[28:29]
	v_cmp_gt_i32_e64 s[24:25], 19, v217
	s_and_b64 s[26:27], s[28:29], s[26:27]
	v_cmp_gt_i32_e64 s[22:23], 18, v217
	s_and_b64 s[24:25], s[26:27], s[24:25]
	v_cmp_gt_i32_e64 s[18:19], 17, v217
	s_and_b64 s[22:23], s[24:25], s[22:23]
	v_cmp_gt_i32_e64 s[16:17], 16, v217
	s_and_b64 s[18:19], s[22:23], s[18:19]
	v_cmp_gt_i32_e64 s[14:15], 11, v217
	s_and_b64 s[16:17], s[18:19], s[16:17]
	v_cmp_gt_i32_e64 s[12:13], 10, v217
	s_and_b64 s[14:15], s[16:17], s[14:15]
	v_cmp_gt_i32_e64 s[10:11], 9, v217
	s_and_b64 s[12:13], s[14:15], s[12:13]
	v_cmp_gt_i32_e64 s[8:9], 8, v217
	s_and_b64 s[10:11], s[12:13], s[10:11]
	v_cmp_gt_i32_e64 s[6:7], 3, v217
	s_and_b64 s[8:9], s[10:11], s[8:9]
	v_cmp_gt_i32_e64 s[4:5], 2, v217
	s_and_b64 s[6:7], s[8:9], s[6:7]
	v_cmp_gt_i32_e64 s[0:1], 1, v217
	s_and_b64 s[4:5], s[6:7], s[4:5]
	v_cmp_gt_i32_e32 vcc, 0, v217
	s_and_b64 s[0:1], s[4:5], s[0:1]
	s_and_b64 vcc, s[0:1], vcc
	v_cndmask_b32_e64 v81, v81, v229, s[34:35]
	v_cndmask_b32_e64 v80, v80, v229, s[30:31]
	v_cndmask_b32_e64 v79, v79, v229, s[28:29]
	v_cndmask_b32_e64 v78, v78, v229, s[26:27]
	v_cndmask_b32_e64 v77, v77, v229, s[24:25]
	v_cndmask_b32_e64 v76, v76, v229, s[22:23]
	v_cndmask_b32_e64 v75, v75, v229, s[18:19]
	v_cndmask_b32_e64 v74, v74, v229, s[16:17]
	v_cndmask_b32_e64 v73, v73, v229, s[14:15]
	v_cndmask_b32_e64 v72, v72, v229, s[12:13]
	v_cndmask_b32_e64 v71, v71, v229, s[10:11]
	v_cndmask_b32_e64 v70, v70, v229, s[8:9]
	v_cndmask_b32_e64 v69, v69, v229, s[6:7]
	v_cndmask_b32_e64 v68, v68, v229, s[4:5]
	v_cndmask_b32_e64 v67, v67, v229, s[0:1]
	v_cndmask_b32_e32 v66, v66, v229, vcc
